# ping-pong attention: waves 0-3 retire their LDS-DMA (vmcnt wait) at the end of the load segment instead of the end of the compute segment
# baseline (speedup 1.0000x reference)
; #define LAS __attribute__((address_space(3)))
; DI s16x4 vtr(const LAS char* p) { return __builtin_bit_cast(s16x4, __builtin_amdgcn_ds_read_tr16_b64_v4i16((LAS v4i16_t*)p)); }
; DI void attn_qk(const LAS char* kb, const bf16x8 (&qf)[4], bf16x8 (&pf)[4], float& l) {
;     f32x16 zero;
; #pragma unroll
;     for (int i = 0; i < 16; ++i) zero[i] = 0.f;
;     bf16x8 k0[4], k1[4];
; #pragma unroll
;     for (int s = 0; s < 4; ++s) k0[s] = *(const LAS bf16x8*)(kb + 32 * s);
; #pragma unroll
;     for (int s = 0; s < 4; ++s) k1[s] = *(const LAS bf16x8*)(kb + 32 * KRS + 32 * s);
;     f32x16 st0 = MFMA32(k0[0], qf[0], zero), st1 = MFMA32(k1[0], qf[0], zero);
; #pragma unroll
;     for (int s = 1; s < 4; ++s) { st0 = MFMA32(k0[s], qf[s], st0); st1 = MFMA32(k1[s], qf[s], st1); }
;     SGB(0x100, 8); SGB(0x008, 8);
;     float sum = 0.f;
; #pragma unroll
;     for (int i = 0; i < 16; ++i) { const float e = __builtin_amdgcn_exp2f(st0[i]); st0[i] = e; sum += e; }
;     pf[0] = pack8(st0, 0); pf[1] = pack8(st0, 1);
; #pragma unroll
;     for (int i = 0; i < 16; ++i) { const float e = __builtin_amdgcn_exp2f(st1[i]); st1[i] = e; sum += e; }
;     pf[2] = pack8(st1, 0); pf[3] = pack8(st1, 1);
;     l += sum;
; }
; DI void attn_pv(const LAS char* vb, const bf16x8 (&pf)[4], f32x16 (&O)[4]) {
;     s16x4 va[8], vc[8];
; #pragma unroll
;     for (int ks = 0; ks < 4; ++ks) { va[2 * ks] = vtr(vb + ks * 16 * VRS); va[2 * ks + 1] = vtr(vb + (ks * 16 + 8) * VRS); }
; #pragma unroll
;     for (int ks = 0; ks < 4; ++ks) { vc[2 * ks] = vtr(vb + ks * 16 * VRS + 64); vc[2 * ks + 1] = vtr(vb + (ks * 16 + 8) * VRS + 64); }
; DI void attn_unit(const Params& p, LAS unsigned char* ldsu, int kind, int b, int h, int u, float lam) {
;     ...
;         auto stage = [&](int t) { if (t >= ntl) t = ntl - 1; const int row0 = t == 0 ? ROW_M : b * SEQ + (t - 1) * 64;
;             dma_tile(lds + (t & 3) * SLOT_B, KB + (size_t)row0 * 512 + hc, VB + (size_t)row0 * 512 + hc, poff, wid); };
;         stage(0); stage(1); stage(2);
;         asm volatile("s_waitcnt vmcnt(10)" ::: "memory");
;         __syncthreads();
;         for (int t = 0; t < ntl; ++t) {
;             stage(t + 3);
;             const LAS char* sp = lds + (t & 3) * SLOT_B;
;             if (t <= my_last) { bf16x8 pf[4]; attn_qk(sp + kboff, qf, pf, l); attn_pv(sp + vboff, pf, O); }
;             BAR_LANDED();
.LBB0_745:
	s_and_b64 vcc, exec, s[0:1]
	s_cbranch_vccz .LattnB
	s_add_i32 s22, s21, 3
	s_min_i32 s24, s22, s6
	s_lshl_b32 s22, s24, 6
	s_add_i32 s22, s17, s22
	s_and_b32 s24, s24, 3
	s_ashr_i32 s23, s22, 31
	s_mul_i32 s24, s24, 0x9400
	s_lshl_b64 s[22:23], s[22:23], 10
	s_add_u32 s25, s16, s22
	s_addc_u32 s26, s18, s23
	s_add_u32 s27, s19, s22
	s_addc_u32 s34, s20, s23
	s_cmp_gt_i32 s21, s29
	s_cbranch_scc1 .LattnA_skip
	s_and_b32 s35, s21, 3
	s_mul_i32 s35, s35, 0x9400
	v_add_u32_e32 v0, s35, v174
	v_add_u32_e32 v14, s35, v134
	ds_read_b128 v[2:5], v0
	ds_read_b128 v[6:9], v0 offset:32
	ds_read_b128 v[10:13], v0 offset:64
	ds_read_b128 v[136:139], v0 offset:96
	ds_read_b128 v[140:143], v0 offset:8704
	ds_read_b128 v[144:147], v0 offset:8736
	ds_read_b128 v[148:151], v0 offset:8768
	ds_read_b128 v[196:199], v0 offset:8800
	ds_read_b64_tr_b16 v[200:201], v14 offset:17408
	ds_read_b64_tr_b16 v[202:203], v14 offset:19968
	ds_read_b64_tr_b16 v[204:205], v14 offset:17472
	ds_read_b64_tr_b16 v[206:207], v14 offset:20032
	ds_read_b64_tr_b16 v[208:209], v14 offset:17536
	ds_read_b64_tr_b16 v[210:211], v14 offset:20096
	ds_read_b64_tr_b16 v[212:213], v14 offset:17600
	ds_read_b64_tr_b16 v[214:215], v14 offset:20160
	ds_read_b64_tr_b16 v[216:217], v14 offset:22528
	ds_read_b64_tr_b16 v[218:219], v14 offset:25088
	ds_read_b64_tr_b16 v[220:221], v14 offset:22592
	ds_read_b64_tr_b16 v[222:223], v14 offset:25152
	ds_read_b64_tr_b16 v[224:225], v14 offset:22656
	ds_read_b64_tr_b16 v[226:227], v14 offset:25216
	ds_read_b64_tr_b16 v[228:229], v14 offset:22720
	ds_read_b64_tr_b16 v[230:231], v14 offset:25280
	ds_read_b64_tr_b16 v[232:233], v14 offset:27648
	ds_read_b64_tr_b16 v[234:235], v14 offset:30208
	ds_read_b64_tr_b16 v[236:237], v14 offset:27712
	ds_read_b64_tr_b16 v[238:239], v14 offset:30272
	ds_read_b64_tr_b16 v[240:241], v14 offset:27776
	ds_read_b64_tr_b16 v[242:243], v14 offset:30336
	ds_read_b64_tr_b16 v[244:245], v14 offset:27840
	ds_read_b64_tr_b16 v[246:247], v14 offset:30400
	ds_read_b64_tr_b16 v[248:249], v14 offset:32768
	ds_read_b64_tr_b16 v[250:251], v14 offset:35328
	ds_read_b64_tr_b16 v[156:157], v14 offset:32832
	ds_read_b64_tr_b16 v[158:159], v14 offset:35392
	ds_read_b64_tr_b16 v[160:161], v14 offset:32896
	ds_read_b64_tr_b16 v[162:163], v14 offset:35456
	ds_read_b64_tr_b16 v[164:165], v14 offset:32960
	ds_read_b64_tr_b16 v[166:167], v14 offset:35520
	s_and_b64 s[22:23], s[0:1], exec
	s_cselect_b32 s23, s26, s34
	s_cselect_b32 s22, s25, s27
	s_add_i32 s35, s24, s7
	s_mov_b32 m0, s35
	s_nop 0
	global_load_lds_dwordx4 v132, s[22:23]
	s_add_i32 s35, s24, s10
	s_addk_i32 s35, 0x400
	s_mov_b32 m0, s35
	s_nop 0
	global_load_lds_dwordx4 v131, s[22:23]
	s_and_b64 s[22:23], exec, s[8:9]
	s_cselect_b32 s23, s26, s34
	s_cselect_b32 s22, s25, s27
	s_add_i32 s35, s24, s11
	s_addk_i32 s35, 0x800
	s_mov_b32 m0, s35
	s_nop 0
	global_load_lds_dwordx4 v130, s[22:23]
	s_add_i32 s35, s24, s12
	s_addk_i32 s35, 0xc00
	s_mov_b32 m0, s35
	s_nop 0
	global_load_lds_dwordx4 v129, s[22:23]
	s_add_i32 s35, s24, s13
	s_addk_i32 s35, 0x1000
	s_mov_b32 m0, s35
	s_nop 0
	global_load_lds_dwordx4 v133, s[22:23]
	s_waitcnt vmcnt(10)
	s_waitcnt lgkmcnt(0)
	s_barrier
	v_mfma_f32_32x32x16_bf16 v[96:111], v[2:5], v[112:115], 0
	v_mfma_f32_32x32x16_bf16 v[96:111], v[6:9], v[116:119], v[96:111]
	v_mfma_f32_32x32x16_bf16 v[96:111], v[10:13], v[120:123], v[96:111]
	v_mfma_f32_32x32x16_bf16 v[96:111], v[136:139], v[124:127], v[96:111]
	s_nop 7
	s_nop 2
	v_mfma_f32_32x32x16_bf16 v[80:95], v[140:143], v[112:115], 0
	v_exp_f32_e32 v96, v96
	v_exp_f32_e32 v97, v97
	s_nop 0
	v_add_f32_e32 v15, v96, v97
	v_mfma_f32_32x32x16_bf16 v[80:95], v[144:147], v[116:119], v[80:95]
	v_exp_f32_e32 v98, v98
	v_exp_f32_e32 v99, v99
	v_cvt_pk_bf16_f32 v96, v96, v97
	v_add_f32_e32 v15, v98, v15
	v_mfma_f32_32x32x16_bf16 v[80:95], v[148:151], v[120:123], v[80:95]
	v_exp_f32_e32 v100, v100
	v_exp_f32_e32 v101, v101
	v_cvt_pk_bf16_f32 v97, v98, v99
	v_add_f32_e32 v15, v99, v15
	v_mfma_f32_32x32x16_bf16 v[80:95], v[196:199], v[124:127], v[80:95]
	v_exp_f32_e32 v102, v102
	v_exp_f32_e32 v103, v103
	v_cvt_pk_bf16_f32 v98, v100, v101
	v_cvt_pk_bf16_f32 v99, v102, v103
	s_nop 1
	v_mfma_f32_32x32x16_bf16 v[64:79], v[200:203], v[96:99], v[64:79]
	v_exp_f32_e32 v104, v104
	v_exp_f32_e32 v105, v105
	v_add_f32_e32 v15, v104, v15
	v_add_f32_e32 v15, v105, v15
	v_mfma_f32_32x32x16_bf16 v[48:63], v[204:207], v[96:99], v[48:63]
	v_exp_f32_e32 v106, v106
	v_exp_f32_e32 v107, v107
	v_cvt_pk_bf16_f32 v104, v104, v105
	v_add_f32_e32 v15, v106, v15
	v_mfma_f32_32x32x16_bf16 v[32:47], v[208:211], v[96:99], v[32:47]
	v_exp_f32_e32 v108, v108
	v_exp_f32_e32 v109, v109
	v_cvt_pk_bf16_f32 v105, v106, v107
	v_add_f32_e32 v15, v107, v15
	v_mfma_f32_32x32x16_bf16 v[16:31], v[212:215], v[96:99], v[16:31]
	v_exp_f32_e32 v110, v110
	v_exp_f32_e32 v111, v111
	v_cvt_pk_bf16_f32 v106, v108, v109
	v_cvt_pk_bf16_f32 v107, v110, v111
	s_nop 1
	v_mfma_f32_32x32x16_bf16 v[64:79], v[216:219], v[104:107], v[64:79]
	v_exp_f32_e32 v80, v80
	v_exp_f32_e32 v81, v81
	v_add_f32_e32 v15, v80, v15
	v_add_f32_e32 v15, v81, v15
	v_mfma_f32_32x32x16_bf16 v[48:63], v[220:223], v[104:107], v[48:63]
	v_exp_f32_e32 v82, v82
	v_exp_f32_e32 v83, v83
	v_cvt_pk_bf16_f32 v80, v80, v81
	v_add_f32_e32 v15, v82, v15
	v_mfma_f32_32x32x16_bf16 v[32:47], v[224:227], v[104:107], v[32:47]
	v_exp_f32_e32 v84, v84
	v_exp_f32_e32 v85, v85
	v_cvt_pk_bf16_f32 v81, v82, v83
	v_add_f32_e32 v15, v83, v15
	v_mfma_f32_32x32x16_bf16 v[16:31], v[228:231], v[104:107], v[16:31]
	v_exp_f32_e32 v86, v86
	v_exp_f32_e32 v87, v87
	v_cvt_pk_bf16_f32 v82, v84, v85
; #define LAS __attribute__((address_space(3)))
; DI s16x4 vtr(const LAS char* p) { return __builtin_bit_cast(s16x4, __builtin_amdgcn_ds_read_tr16_b64_v4i16((LAS v4i16_t*)p)); }
; DI bf16x8 cat4(s16x4 lo, s16x4 hi) { return __builtin_shufflevector(lo, hi, 0, 1, 2, 3, 4, 5, 6, 7); }
; #define MFMA32(a, b, c) __builtin_amdgcn_mfma_f32_32x32x16_bf16((a), (b), (c), 0, 0, 0)
; #define SGB(mask, n) __builtin_amdgcn_sched_group_barrier((mask), (n), 0)
; #define BAR_LANDED() asm volatile("s_waitcnt vmcnt(10)\n\ts_barrier" ::: "memory")
; DI void attn_pv(const LAS char* vb, const bf16x8 (&pf)[4], f32x16 (&O)[4]) {
;     ...
;     for (int ks = 0; ks < 4; ++ks) O[0] = MFMA32(cat4(va[2 * ks], va[2 * ks + 1]), pf[ks], O[0]);
; #pragma unroll
;     for (int ks = 0; ks < 4; ++ks) { va[2 * ks] = vtr(vb + ks * 16 * VRS + 128); va[2 * ks + 1] = vtr(vb + (ks * 16 + 8) * VRS + 128); }
;     SGB(0x100, 16); SGB(0x008, 4); SGB(0x100, 8);
; #pragma unroll
;     for (int ks = 0; ks < 4; ++ks) O[1] = MFMA32(cat4(vc[2 * ks], vc[2 * ks + 1]), pf[ks], O[1]);
; #pragma unroll
;     for (int ks = 0; ks < 4; ++ks) { vc[2 * ks] = vtr(vb + ks * 16 * VRS + 192); vc[2 * ks + 1] = vtr(vb + (ks * 16 + 8) * VRS + 192); }
;     SGB(0x008, 4); SGB(0x100, 8);
; #pragma unroll
;     for (int ks = 0; ks < 4; ++ks) O[2] = MFMA32(cat4(va[2 * ks], va[2 * ks + 1]), pf[ks], O[2]);
;     SGB(0x008, 4);
; #pragma unroll
;     for (int ks = 0; ks < 4; ++ks) O[3] = MFMA32(cat4(vc[2 * ks], vc[2 * ks + 1]), pf[ks], O[3]);
;     SGB(0x008, 4);
; }
; DI void attn_unit(const Params& p, LAS unsigned char* ldsu, int kind, int b, int h, int u, float lam) {
;     ...
;         auto stage = [&](int t) { if (t >= ntl) t = ntl - 1; const int row0 = t == 0 ? ROW_M : b * SEQ + (t - 1) * 64;
;             dma_tile(lds + (t & 3) * SLOT_B, KB + (size_t)row0 * 512 + hc, VB + (size_t)row0 * 512 + hc, poff, wid); };
;         stage(0); stage(1); stage(2);
;         asm volatile("s_waitcnt vmcnt(10)" ::: "memory");
;         __syncthreads();
;         for (int t = 0; t < ntl; ++t) {
;             stage(t + 3);
;             const LAS char* sp = lds + (t & 3) * SLOT_B;
;             if (t <= my_last) { bf16x8 pf[4]; attn_qk(sp + kboff, qf, pf, l); attn_pv(sp + vboff, pf, O); }
;             BAR_LANDED();
	v_cvt_pk_bf16_f32 v83, v86, v87
	s_nop 1
	v_mfma_f32_32x32x16_bf16 v[64:79], v[232:235], v[80:83], v[64:79]
	v_exp_f32_e32 v88, v88
	v_exp_f32_e32 v89, v89
	v_add_f32_e32 v15, v88, v15
	v_add_f32_e32 v15, v89, v15
	v_mfma_f32_32x32x16_bf16 v[48:63], v[236:239], v[80:83], v[48:63]
	v_exp_f32_e32 v90, v90
	v_exp_f32_e32 v91, v91
	v_cvt_pk_bf16_f32 v88, v88, v89
	v_add_f32_e32 v15, v90, v15
	v_mfma_f32_32x32x16_bf16 v[32:47], v[240:243], v[80:83], v[32:47]
	v_exp_f32_e32 v92, v92
	v_exp_f32_e32 v93, v93
	v_cvt_pk_bf16_f32 v89, v90, v91
	v_add_f32_e32 v15, v91, v15
	v_mfma_f32_32x32x16_bf16 v[16:31], v[244:247], v[80:83], v[16:31]
	v_exp_f32_e32 v94, v94
	v_exp_f32_e32 v95, v95
	v_cvt_pk_bf16_f32 v90, v92, v93
	v_cvt_pk_bf16_f32 v91, v94, v95
	s_nop 1
	v_mfma_f32_32x32x16_bf16 v[64:79], v[248:251], v[88:91], v[64:79]
	v_add_f32_e32 v15, v100, v15
	v_add_f32_e32 v15, v101, v15
	v_add_f32_e32 v15, v102, v15
	v_add_f32_e32 v15, v103, v15
	v_mfma_f32_32x32x16_bf16 v[48:63], v[156:159], v[88:91], v[48:63]
	v_add_f32_e32 v15, v108, v15
	v_add_f32_e32 v15, v109, v15
	v_add_f32_e32 v15, v110, v15
	v_add_f32_e32 v15, v111, v15
	v_mfma_f32_32x32x16_bf16 v[32:47], v[160:163], v[88:91], v[32:47]
	v_add_f32_e32 v15, v84, v15
	v_add_f32_e32 v15, v85, v15
	v_add_f32_e32 v15, v86, v15
	v_add_f32_e32 v15, v87, v15
	v_mfma_f32_32x32x16_bf16 v[16:31], v[164:167], v[88:91], v[16:31]
	v_add_f32_e32 v15, v92, v15
	v_add_f32_e32 v15, v93, v15
	v_add_f32_e32 v15, v94, v15
	v_add_f32_e32 v15, v95, v15
	v_add_f32_e32 v175, v175, v15
	s_barrier
	s_branch .LBB0_744
.LattnA_skip:
	s_and_b64 s[22:23], s[0:1], exec
	s_cselect_b32 s23, s26, s34
	s_cselect_b32 s22, s25, s27
	s_add_i32 s35, s24, s7
	s_mov_b32 m0, s35
	s_nop 0
	global_load_lds_dwordx4 v132, s[22:23]
	s_add_i32 s35, s24, s10
	s_addk_i32 s35, 0x400
	s_mov_b32 m0, s35
	s_nop 0
	global_load_lds_dwordx4 v131, s[22:23]
	s_and_b64 s[22:23], exec, s[8:9]
	s_cselect_b32 s23, s26, s34
	s_cselect_b32 s22, s25, s27
	s_add_i32 s35, s24, s11
	s_addk_i32 s35, 0x800
	s_mov_b32 m0, s35
	s_nop 0
	global_load_lds_dwordx4 v130, s[22:23]
	s_add_i32 s35, s24, s12
	s_addk_i32 s35, 0xc00
	s_mov_b32 m0, s35
	s_nop 0
	global_load_lds_dwordx4 v129, s[22:23]
	s_add_i32 s35, s24, s13
	s_addk_i32 s35, 0x1000
	s_mov_b32 m0, s35
	s_nop 0
	global_load_lds_dwordx4 v133, s[22:23]
	s_waitcnt vmcnt(10)
	s_barrier
	s_barrier
	s_branch .LBB0_744
.LattnB:
	s_add_i32 s22, s21, 3
	s_min_i32 s24, s22, s6
	s_lshl_b32 s22, s24, 6
	s_add_i32 s22, s17, s22
	s_and_b32 s24, s24, 3
	s_ashr_i32 s23, s22, 31
	s_mul_i32 s24, s24, 0x9400
	s_lshl_b64 s[22:23], s[22:23], 10
	s_add_u32 s25, s16, s22
	s_addc_u32 s26, s18, s23
	s_add_u32 s27, s19, s22
	s_addc_u32 s34, s20, s23
	s_cmp_gt_i32 s21, s29
	s_cbranch_scc1 .LattnB_skip
	s_and_b32 s35, s21, 3
	s_mul_i32 s35, s35, 0x9400
	v_add_u32_e32 v0, s35, v174
	v_add_u32_e32 v14, s35, v134
	ds_read_b128 v[2:5], v0
	ds_read_b128 v[6:9], v0 offset:32
	ds_read_b128 v[10:13], v0 offset:64
	ds_read_b128 v[136:139], v0 offset:96
	ds_read_b128 v[140:143], v0 offset:8704
	ds_read_b128 v[144:147], v0 offset:8736
	ds_read_b128 v[148:151], v0 offset:8768
	ds_read_b128 v[196:199], v0 offset:8800
	ds_read_b64_tr_b16 v[200:201], v14 offset:17408
	ds_read_b64_tr_b16 v[202:203], v14 offset:19968
	ds_read_b64_tr_b16 v[204:205], v14 offset:17472
	ds_read_b64_tr_b16 v[206:207], v14 offset:20032
	ds_read_b64_tr_b16 v[208:209], v14 offset:17536
	ds_read_b64_tr_b16 v[210:211], v14 offset:20096
	ds_read_b64_tr_b16 v[212:213], v14 offset:17600
	ds_read_b64_tr_b16 v[214:215], v14 offset:20160
	ds_read_b64_tr_b16 v[216:217], v14 offset:22528
	ds_read_b64_tr_b16 v[218:219], v14 offset:25088
	ds_read_b64_tr_b16 v[220:221], v14 offset:22592
	ds_read_b64_tr_b16 v[222:223], v14 offset:25152
	ds_read_b64_tr_b16 v[224:225], v14 offset:22656
	ds_read_b64_tr_b16 v[226:227], v14 offset:25216
	ds_read_b64_tr_b16 v[228:229], v14 offset:22720
	ds_read_b64_tr_b16 v[230:231], v14 offset:25280
	ds_read_b64_tr_b16 v[232:233], v14 offset:27648
	ds_read_b64_tr_b16 v[234:235], v14 offset:30208
	ds_read_b64_tr_b16 v[236:237], v14 offset:27712
	ds_read_b64_tr_b16 v[238:239], v14 offset:30272
	ds_read_b64_tr_b16 v[240:241], v14 offset:27776
	ds_read_b64_tr_b16 v[242:243], v14 offset:30336
	ds_read_b64_tr_b16 v[244:245], v14 offset:27840
	ds_read_b64_tr_b16 v[246:247], v14 offset:30400
	ds_read_b64_tr_b16 v[248:249], v14 offset:32768
	ds_read_b64_tr_b16 v[250:251], v14 offset:35328
	ds_read_b64_tr_b16 v[156:157], v14 offset:32832
	ds_read_b64_tr_b16 v[158:159], v14 offset:35392
	ds_read_b64_tr_b16 v[160:161], v14 offset:32896
	ds_read_b64_tr_b16 v[162:163], v14 offset:35456
	ds_read_b64_tr_b16 v[164:165], v14 offset:32960
	ds_read_b64_tr_b16 v[166:167], v14 offset:35520
	s_and_b64 s[22:23], s[0:1], exec
	s_cselect_b32 s23, s26, s34
	s_cselect_b32 s22, s25, s27
	s_add_i32 s35, s24, s7
	s_mov_b32 m0, s35
	s_nop 0
	global_load_lds_dwordx4 v132, s[22:23]
	s_add_i32 s35, s24, s10
	s_addk_i32 s35, 0x400
	s_mov_b32 m0, s35
	s_nop 0
	global_load_lds_dwordx4 v131, s[22:23]
	s_and_b64 s[22:23], exec, s[8:9]
	s_cselect_b32 s23, s26, s34
	s_cselect_b32 s22, s25, s27
	s_add_i32 s35, s24, s11
	s_addk_i32 s35, 0x800
	s_mov_b32 m0, s35
	s_nop 0
	global_load_lds_dwordx4 v130, s[22:23]
	s_add_i32 s35, s24, s12
	s_addk_i32 s35, 0xc00
	s_mov_b32 m0, s35
	s_nop 0
	global_load_lds_dwordx4 v129, s[22:23]
	s_add_i32 s35, s24, s13
	s_addk_i32 s35, 0x1000
	s_mov_b32 m0, s35
	s_nop 0
	global_load_lds_dwordx4 v133, s[22:23]
	s_waitcnt vmcnt(10)
	s_waitcnt lgkmcnt(0)
	s_barrier
; DI void attn_qk(const LAS char* kb, const bf16x8 (&qf)[4], bf16x8 (&pf)[4], float& l) {
;     f32x16 zero;
; #pragma unroll
;     for (int i = 0; i < 16; ++i) zero[i] = 0.f;
;     bf16x8 k0[4], k1[4];
; #pragma unroll
;     for (int s = 0; s < 4; ++s) k0[s] = *(const LAS bf16x8*)(kb + 32 * s);
; #pragma unroll
;     for (int s = 0; s < 4; ++s) k1[s] = *(const LAS bf16x8*)(kb + 32 * KRS + 32 * s);
;     f32x16 st0 = MFMA32(k0[0], qf[0], zero), st1 = MFMA32(k1[0], qf[0], zero);
; #pragma unroll
;     for (int s = 1; s < 4; ++s) { st0 = MFMA32(k0[s], qf[s], st0); st1 = MFMA32(k1[s], qf[s], st1); }
;     SGB(0x100, 8); SGB(0x008, 8);
;     float sum = 0.f;
; #pragma unroll
;     for (int i = 0; i < 16; ++i) { const float e = __builtin_amdgcn_exp2f(st0[i]); st0[i] = e; sum += e; }
;     pf[0] = pack8(st0, 0); pf[1] = pack8(st0, 1);
; #pragma unroll
;     for (int i = 0; i < 16; ++i) { const float e = __builtin_amdgcn_exp2f(st1[i]); st1[i] = e; sum += e; }
;     pf[2] = pack8(st1, 0); pf[3] = pack8(st1, 1);
;     l += sum;
; }
; DI void attn_pv(const LAS char* vb, const bf16x8 (&pf)[4], f32x16 (&O)[4]) {
;     s16x4 va[8], vc[8];
; #pragma unroll
;     for (int ks = 0; ks < 4; ++ks) { va[2 * ks] = vtr(vb + ks * 16 * VRS); va[2 * ks + 1] = vtr(vb + (ks * 16 + 8) * VRS); }
; #pragma unroll
;     for (int ks = 0; ks < 4; ++ks) { vc[2 * ks] = vtr(vb + ks * 16 * VRS + 64); vc[2 * ks + 1] = vtr(vb + (ks * 16 + 8) * VRS + 64); }
; #pragma unroll
;     for (int ks = 0; ks < 4; ++ks) O[0] = MFMA32(cat4(va[2 * ks], va[2 * ks + 1]), pf[ks], O[0]);
; #pragma unroll
;     for (int ks = 0; ks < 4; ++ks) { va[2 * ks] = vtr(vb + ks * 16 * VRS + 128); va[2 * ks + 1] = vtr(vb + (ks * 16 + 8) * VRS + 128); }
;     SGB(0x100, 16); SGB(0x008, 4); SGB(0x100, 8);
; #pragma unroll
;     for (int ks = 0; ks < 4; ++ks) O[1] = MFMA32(cat4(vc[2 * ks], vc[2 * ks + 1]), pf[ks], O[1]);
; #pragma unroll
;     for (int ks = 0; ks < 4; ++ks) { vc[2 * ks] = vtr(vb + ks * 16 * VRS + 192); vc[2 * ks + 1] = vtr(vb + (ks * 16 + 8) * VRS + 192); }
;     SGB(0x008, 4); SGB(0x100, 8);
; #pragma unroll
;     for (int ks = 0; ks < 4; ++ks) O[2] = MFMA32(cat4(va[2 * ks], va[2 * ks + 1]), pf[ks], O[2]);
;     SGB(0x008, 4);
; #pragma unroll
;     for (int ks = 0; ks < 4; ++ks) O[3] = MFMA32(cat4(vc[2 * ks], vc[2 * ks + 1]), pf[ks], O[3]);
;     SGB(0x008, 4);
; }
	v_mfma_f32_32x32x16_bf16 v[96:111], v[2:5], v[112:115], 0
	v_mfma_f32_32x32x16_bf16 v[96:111], v[6:9], v[116:119], v[96:111]
	v_mfma_f32_32x32x16_bf16 v[96:111], v[10:13], v[120:123], v[96:111]
	v_mfma_f32_32x32x16_bf16 v[96:111], v[136:139], v[124:127], v[96:111]
	s_nop 7
	s_nop 2
	v_mfma_f32_32x32x16_bf16 v[80:95], v[140:143], v[112:115], 0
	v_exp_f32_e32 v96, v96
	v_exp_f32_e32 v97, v97
	s_nop 0
	v_add_f32_e32 v15, v96, v97
	v_mfma_f32_32x32x16_bf16 v[80:95], v[144:147], v[116:119], v[80:95]
	v_exp_f32_e32 v98, v98
	v_exp_f32_e32 v99, v99
	v_cvt_pk_bf16_f32 v96, v96, v97
	v_add_f32_e32 v15, v98, v15
	v_mfma_f32_32x32x16_bf16 v[80:95], v[148:151], v[120:123], v[80:95]
	v_exp_f32_e32 v100, v100
	v_exp_f32_e32 v101, v101
	v_cvt_pk_bf16_f32 v97, v98, v99
	v_add_f32_e32 v15, v99, v15
	v_mfma_f32_32x32x16_bf16 v[80:95], v[196:199], v[124:127], v[80:95]
	v_exp_f32_e32 v102, v102
	v_exp_f32_e32 v103, v103
	v_cvt_pk_bf16_f32 v98, v100, v101
	v_cvt_pk_bf16_f32 v99, v102, v103
	s_nop 1
	v_mfma_f32_32x32x16_bf16 v[64:79], v[200:203], v[96:99], v[64:79]
	v_exp_f32_e32 v104, v104
	v_exp_f32_e32 v105, v105
	v_add_f32_e32 v15, v104, v15
	v_add_f32_e32 v15, v105, v15
	v_mfma_f32_32x32x16_bf16 v[48:63], v[204:207], v[96:99], v[48:63]
	v_exp_f32_e32 v106, v106
	v_exp_f32_e32 v107, v107
	v_cvt_pk_bf16_f32 v104, v104, v105
	v_add_f32_e32 v15, v106, v15
	v_mfma_f32_32x32x16_bf16 v[32:47], v[208:211], v[96:99], v[32:47]
	v_exp_f32_e32 v108, v108
	v_exp_f32_e32 v109, v109
	v_cvt_pk_bf16_f32 v105, v106, v107
	v_add_f32_e32 v15, v107, v15
	v_mfma_f32_32x32x16_bf16 v[16:31], v[212:215], v[96:99], v[16:31]
	v_exp_f32_e32 v110, v110
	v_exp_f32_e32 v111, v111
	v_cvt_pk_bf16_f32 v106, v108, v109
	v_cvt_pk_bf16_f32 v107, v110, v111
	s_nop 1
	v_mfma_f32_32x32x16_bf16 v[64:79], v[216:219], v[104:107], v[64:79]
	v_exp_f32_e32 v80, v80
	v_exp_f32_e32 v81, v81
	v_add_f32_e32 v15, v80, v15
	v_add_f32_e32 v15, v81, v15
	v_mfma_f32_32x32x16_bf16 v[48:63], v[220:223], v[104:107], v[48:63]
	v_exp_f32_e32 v82, v82
	v_exp_f32_e32 v83, v83
	v_cvt_pk_bf16_f32 v80, v80, v81
	v_add_f32_e32 v15, v82, v15
	v_mfma_f32_32x32x16_bf16 v[32:47], v[224:227], v[104:107], v[32:47]
	v_exp_f32_e32 v84, v84
	v_exp_f32_e32 v85, v85
	v_cvt_pk_bf16_f32 v81, v82, v83
	v_add_f32_e32 v15, v83, v15
	v_mfma_f32_32x32x16_bf16 v[16:31], v[228:231], v[104:107], v[16:31]
	v_exp_f32_e32 v86, v86
	v_exp_f32_e32 v87, v87
	v_cvt_pk_bf16_f32 v82, v84, v85
	v_cvt_pk_bf16_f32 v83, v86, v87
	s_nop 1
	v_mfma_f32_32x32x16_bf16 v[64:79], v[232:235], v[80:83], v[64:79]
	v_exp_f32_e32 v88, v88
	v_exp_f32_e32 v89, v89
	v_add_f32_e32 v15, v88, v15
	v_add_f32_e32 v15, v89, v15
	v_mfma_f32_32x32x16_bf16 v[48:63], v[236:239], v[80:83], v[48:63]
	v_exp_f32_e32 v90, v90
	v_exp_f32_e32 v91, v91
	v_cvt_pk_bf16_f32 v88, v88, v89
	v_add_f32_e32 v15, v90, v15
	v_mfma_f32_32x32x16_bf16 v[32:47], v[240:243], v[80:83], v[32:47]
	v_exp_f32_e32 v92, v92
	v_exp_f32_e32 v93, v93
	v_cvt_pk_bf16_f32 v89, v90, v91
	v_add_f32_e32 v15, v91, v15
	v_mfma_f32_32x32x16_bf16 v[16:31], v[244:247], v[80:83], v[16:31]
	v_exp_f32_e32 v94, v94
	v_exp_f32_e32 v95, v95
	v_cvt_pk_bf16_f32 v90, v92, v93
	v_cvt_pk_bf16_f32 v91, v94, v95
	s_nop 1
	v_mfma_f32_32x32x16_bf16 v[64:79], v[248:251], v[88:91], v[64:79]
	v_add_f32_e32 v15, v100, v15
	v_add_f32_e32 v15, v101, v15
	v_add_f32_e32 v15, v102, v15
	v_add_f32_e32 v15, v103, v15
	v_mfma_f32_32x32x16_bf16 v[48:63], v[156:159], v[88:91], v[48:63]
	v_add_f32_e32 v15, v108, v15
	v_add_f32_e32 v15, v109, v15
	v_add_f32_e32 v15, v110, v15
	v_add_f32_e32 v15, v111, v15
	v_mfma_f32_32x32x16_bf16 v[32:47], v[160:163], v[88:91], v[32:47]
	v_add_f32_e32 v15, v84, v15
	v_add_f32_e32 v15, v85, v15
	v_add_f32_e32 v15, v86, v15
	v_add_f32_e32 v15, v87, v15
	v_mfma_f32_32x32x16_bf16 v[16:31], v[164:167], v[88:91], v[16:31]
	v_add_f32_e32 v15, v92, v15
	v_add_f32_e32 v15, v93, v15
	v_add_f32_e32 v15, v94, v15
	v_add_f32_e32 v15, v95, v15
	v_add_f32_e32 v175, v175, v15
	s_barrier
	s_branch .LBB0_744
